# MLA unit prologue: all 12 Q loads issued together into their final registers, counted waits (was load-wait-convert one at a time)
# speedup vs baseline: 1.0241x; 1.0012x over previous
; __device__ __forceinline__ float bf2f(unsigned h) { return __uint_as_float(h << 16); }
; __device__ __forceinline__ void mla_unit(char* lds, const bf16_t* __restrict__ Qp, const bf16_t* __restrict__ Knp, const bf16_t* __restrict__ Vp, ...
;     ...
;   const bf16_t* Qw = Qp + (long)(wid * QBLK + r32) * LDQ + hi * 8;
; #pragma unroll
;   for (int d0 = 0; d0 < 8; ++d0) { const u32x4 raw = *reinterpret_cast<const u32x4*>(Qw + d0 * 16); u32x4 w;
; #pragma unroll
;     for (int p = 0; p < 4; ++p) w[p] = cvtpk(bf2f(raw[p] & 0xffffu) * C, bf2f(raw[p] >> 16) * C);
;     qr[d0] = *reinterpret_cast<bf16x8*>(&w); }
.LBB0_238:
	s_lshl_b32 s1, s74, 8
	s_lshl_b64 s[64:65], s[6:7], 13
	s_and_b32 s1, s1, 0x1f00
	s_or_b32 s64, s64, s1
	s_mul_hi_u32 s6, s64, 0x1800
	s_mul_i32 s7, s65, 0x1800
	s_mul_i32 s5, s64, 0x1800
	s_add_i32 s6, s6, s7
	v_readlane_b32 s7, v254, 60
	s_add_u32 s5, s7, s5
	v_readlane_b32 s7, v254, 61
	s_addc_u32 s7, s7, s6
	s_mul_i32 s6, s38, 0x180
	s_add_u32 s6, s5, s6
	s_addc_u32 s7, s7, 0
	v_and_b32_e32 v196, 31, v50
	s_lshl_b32 s39, s8, 5
	v_or_b32_e32 v1, s39, v196
	v_mov_b64_e32 v[2:3], s[6:7]
	s_movk_i32 s5, 0x1800
	v_mad_i64_i32 v[2:3], s[6:7], v1, s5, v[2:3]
	v_lshlrev_b32_e32 v194, 4, v49
	v_mov_b32_e32 v195, v0
	v_lshl_add_u64 v[2:3], v[2:3], 0, v[194:195]
	global_load_dwordx4 v[130:133], v[2:3], off
	global_load_dwordx4 v[134:137], v[2:3], off offset:32
	global_load_dwordx4 v[138:141], v[2:3], off offset:64
	global_load_dwordx4 v[142:145], v[2:3], off offset:96
	global_load_dwordx4 v[154:157], v[2:3], off offset:128
	global_load_dwordx4 v[150:153], v[2:3], off offset:160
	global_load_dwordx4 v[146:149], v[2:3], off offset:192
	global_load_dwordx4 v[158:161], v[2:3], off offset:224
	global_load_dwordx4 v[162:165], v[2:3], off offset:256
	global_load_dwordx4 v[166:169], v[2:3], off offset:288
	global_load_dwordx4 v[170:173], v[2:3], off offset:320
	global_load_dwordx4 v[174:177], v[2:3], off offset:352
	s_mov_b32 s6, 0x3dd53b94
	v_lshlrev_b32_e32 v204, 8, v196
	v_and_b32_e32 v51, 0xf0, v48
	v_add_u32_e32 v66, 0, v204
	s_waitcnt vmcnt(20)
	v_xad_u32 v56, v194, v51, v66
	v_lshlrev_b32_e32 v205, 7, v196
	s_and_b32 s0, s0, 0x3fffffc0
	s_lshl_b32 s0, s0, 2
	s_add_i32 s33, s0, 0
	s_add_i32 s33, s33, 0x1e000
	v_lshl_add_u32 v200, v196, 2, s33
	s_waitcnt vmcnt(11)
	v_lshlrev_b32_e32 v1, 16, v130
	v_and_b32_e32 v4, 0xffff0000, v130
	v_lshlrev_b32_e32 v8, 16, v131
	v_and_b32_e32 v5, 0xffff0000, v131
	v_lshlrev_b32_e32 v9, 16, v132
	v_and_b32_e32 v6, 0xffff0000, v132
	v_lshlrev_b32_e32 v10, 16, v133
	v_and_b32_e32 v7, 0xffff0000, v133
	v_mul_f32_e32 v4, 0x3dd53b94, v4
	v_mul_f32_e32 v5, 0x3dd53b94, v5
	v_mul_f32_e32 v6, 0x3dd53b94, v6
	v_mul_f32_e32 v7, 0x3dd53b94, v7
	v_mul_f32_e32 v1, 0x3dd53b94, v1
	v_mul_f32_e32 v8, 0x3dd53b94, v8
	v_mul_f32_e32 v9, 0x3dd53b94, v9
	v_mul_f32_e32 v10, 0x3dd53b94, v10
	v_cvt_pk_bf16_f32 v130, v1, v4
	v_cvt_pk_bf16_f32 v131, v8, v5
	v_cvt_pk_bf16_f32 v132, v9, v6
	v_cvt_pk_bf16_f32 v133, v10, v7
	s_waitcnt vmcnt(10)
	v_lshlrev_b32_e32 v1, 16, v134
	v_and_b32_e32 v4, 0xffff0000, v134
	v_lshlrev_b32_e32 v8, 16, v135
	v_and_b32_e32 v5, 0xffff0000, v135
	v_lshlrev_b32_e32 v9, 16, v136
	v_and_b32_e32 v6, 0xffff0000, v136
	v_lshlrev_b32_e32 v10, 16, v137
	v_and_b32_e32 v7, 0xffff0000, v137
	v_mul_f32_e32 v4, 0x3dd53b94, v4
	v_mul_f32_e32 v5, 0x3dd53b94, v5
	v_mul_f32_e32 v6, 0x3dd53b94, v6
	v_mul_f32_e32 v7, 0x3dd53b94, v7
	v_mul_f32_e32 v1, 0x3dd53b94, v1
	v_mul_f32_e32 v8, 0x3dd53b94, v8
	v_mul_f32_e32 v9, 0x3dd53b94, v9
	v_mul_f32_e32 v10, 0x3dd53b94, v10
	v_cvt_pk_bf16_f32 v134, v1, v4
	v_cvt_pk_bf16_f32 v135, v8, v5
	v_cvt_pk_bf16_f32 v136, v9, v6
	v_cvt_pk_bf16_f32 v137, v10, v7
	s_waitcnt vmcnt(9)
	v_lshlrev_b32_e32 v1, 16, v138
	v_and_b32_e32 v4, 0xffff0000, v138
	v_lshlrev_b32_e32 v8, 16, v139
	v_and_b32_e32 v5, 0xffff0000, v139
	v_lshlrev_b32_e32 v9, 16, v140
	v_and_b32_e32 v6, 0xffff0000, v140
	v_lshlrev_b32_e32 v10, 16, v141
	v_and_b32_e32 v7, 0xffff0000, v141
	v_mul_f32_e32 v4, 0x3dd53b94, v4
	v_mul_f32_e32 v5, 0x3dd53b94, v5
	v_mul_f32_e32 v6, 0x3dd53b94, v6
	v_mul_f32_e32 v7, 0x3dd53b94, v7
	v_mul_f32_e32 v1, 0x3dd53b94, v1
	v_mul_f32_e32 v8, 0x3dd53b94, v8
	v_mul_f32_e32 v9, 0x3dd53b94, v9
	v_mul_f32_e32 v10, 0x3dd53b94, v10
	v_cvt_pk_bf16_f32 v138, v1, v4
	v_cvt_pk_bf16_f32 v139, v8, v5
	v_cvt_pk_bf16_f32 v140, v9, v6
	v_cvt_pk_bf16_f32 v141, v10, v7
	s_waitcnt vmcnt(8)
	v_lshlrev_b32_e32 v1, 16, v142
	v_and_b32_e32 v4, 0xffff0000, v142
	v_lshlrev_b32_e32 v8, 16, v143
	v_and_b32_e32 v5, 0xffff0000, v143
	v_lshlrev_b32_e32 v9, 16, v144
	v_and_b32_e32 v6, 0xffff0000, v144
	v_lshlrev_b32_e32 v10, 16, v145
	v_and_b32_e32 v7, 0xffff0000, v145
	v_mul_f32_e32 v4, 0x3dd53b94, v4
	v_mul_f32_e32 v5, 0x3dd53b94, v5
	v_mul_f32_e32 v6, 0x3dd53b94, v6
	v_mul_f32_e32 v7, 0x3dd53b94, v7
	v_mul_f32_e32 v1, 0x3dd53b94, v1
	v_mul_f32_e32 v8, 0x3dd53b94, v8
	v_mul_f32_e32 v9, 0x3dd53b94, v9
	v_mul_f32_e32 v10, 0x3dd53b94, v10
	v_cvt_pk_bf16_f32 v142, v1, v4
	v_cvt_pk_bf16_f32 v143, v8, v5
	v_cvt_pk_bf16_f32 v144, v9, v6
	v_cvt_pk_bf16_f32 v145, v10, v7
	s_waitcnt vmcnt(7)
	v_lshlrev_b32_e32 v1, 16, v154
	v_and_b32_e32 v4, 0xffff0000, v154
	v_lshlrev_b32_e32 v8, 16, v155
	v_and_b32_e32 v5, 0xffff0000, v155
	v_lshlrev_b32_e32 v9, 16, v156
	v_and_b32_e32 v6, 0xffff0000, v156
	v_lshlrev_b32_e32 v10, 16, v157
	v_and_b32_e32 v7, 0xffff0000, v157
	v_mul_f32_e32 v4, 0x3dd53b94, v4
	v_mul_f32_e32 v5, 0x3dd53b94, v5
	v_mul_f32_e32 v6, 0x3dd53b94, v6
	v_mul_f32_e32 v7, 0x3dd53b94, v7
	v_mul_f32_e32 v1, 0x3dd53b94, v1
	v_mul_f32_e32 v8, 0x3dd53b94, v8
	v_mul_f32_e32 v9, 0x3dd53b94, v9
	v_mul_f32_e32 v10, 0x3dd53b94, v10
	v_cvt_pk_bf16_f32 v154, v1, v4
	v_cvt_pk_bf16_f32 v155, v8, v5
	v_cvt_pk_bf16_f32 v156, v9, v6
	v_cvt_pk_bf16_f32 v157, v10, v7
	s_waitcnt vmcnt(6)
	v_lshlrev_b32_e32 v1, 16, v150
	v_and_b32_e32 v4, 0xffff0000, v150
	v_lshlrev_b32_e32 v8, 16, v151
	v_and_b32_e32 v5, 0xffff0000, v151
	v_lshlrev_b32_e32 v9, 16, v152
	v_and_b32_e32 v6, 0xffff0000, v152
	v_lshlrev_b32_e32 v10, 16, v153
	v_and_b32_e32 v7, 0xffff0000, v153
	v_mul_f32_e32 v4, 0x3dd53b94, v4
	v_mul_f32_e32 v5, 0x3dd53b94, v5
	v_mul_f32_e32 v6, 0x3dd53b94, v6
	v_mul_f32_e32 v7, 0x3dd53b94, v7
	v_mul_f32_e32 v1, 0x3dd53b94, v1
	v_mul_f32_e32 v8, 0x3dd53b94, v8
	v_mul_f32_e32 v9, 0x3dd53b94, v9
	v_mul_f32_e32 v10, 0x3dd53b94, v10
	v_cvt_pk_bf16_f32 v150, v1, v4
	v_cvt_pk_bf16_f32 v151, v8, v5
	v_cvt_pk_bf16_f32 v152, v9, v6
	v_cvt_pk_bf16_f32 v153, v10, v7
	s_waitcnt vmcnt(5)
; __device__ __forceinline__ float bf2f(unsigned h) { return __uint_as_float(h << 16); }
; __device__ __forceinline__ void mla_unit(char* lds, const bf16_t* __restrict__ Qp, const bf16_t* __restrict__ Knp, const bf16_t* __restrict__ Vp, ...
;     ...
;   for (int d0 = 0; d0 < 8; ++d0) { const u32x4 raw = *reinterpret_cast<const u32x4*>(Qw + d0 * 16); u32x4 w;
; #pragma unroll
;     for (int p = 0; p < 4; ++p) w[p] = cvtpk(bf2f(raw[p] & 0xffffu) * C, bf2f(raw[p] >> 16) * C);
;     qr[d0] = *reinterpret_cast<bf16x8*>(&w); }
;   { const int pos = pos0 + wid * QBLK + r32;
; #pragma unroll
;     for (int d0 = 0; d0 < 4; ++d0) {
;       const u32x4 raw = *reinterpret_cast<const u32x4*>(Qw + 128 + d0 * 16);
;       const int i0 = d0 * 8 + hi * 4;
;       const f32x4 cc = *reinterpret_cast<const f32x4*>(cs_tab + pos * 32 + i0) * C, ss = *reinterpret_cast<const f32x4*>(sn_tab + pos * 32 + i0) * C;
;       u32x4 w;
; #pragma unroll
;       for (int p = 0; p < 4; ++p) { const float x1 = bf2f(raw[p] & 0xffffu), x2 = bf2f(raw[p] >> 16); w[p] = cvtpk(x1 * cc[p] - x2 * ss[p], x1 * ss[p] + x2 * cc[p]); }
;       qr[8 + d0] = *reinterpret_cast<bf16x8*>(&w);
;     } }
	v_lshlrev_b32_e32 v8, 16, v147
	v_lshlrev_b32_e32 v9, 16, v148
	v_and_b32_e32 v6, 0xffff0000, v148
	v_lshlrev_b32_e32 v10, 16, v149
	v_and_b32_e32 v7, 0xffff0000, v149
	v_lshlrev_b32_e32 v1, 16, v146
	v_and_b32_e32 v4, 0xffff0000, v146
	v_and_b32_e32 v5, 0xffff0000, v147
	v_mul_f32_e32 v8, 0x3dd53b94, v8
	v_mul_f32_e32 v9, 0x3dd53b94, v9
	v_mul_f32_e32 v6, 0x3dd53b94, v6
	v_mul_f32_e32 v7, 0x3dd53b94, v7
	v_mul_f32_e32 v1, 0x3dd53b94, v1
	v_mul_f32_e32 v4, 0x3dd53b94, v4
	v_mul_f32_e32 v5, 0x3dd53b94, v5
	v_mul_f32_e32 v10, 0x3dd53b94, v10
	v_cvt_pk_bf16_f32 v146, v1, v4
	v_cvt_pk_bf16_f32 v147, v8, v5
	v_cvt_pk_bf16_f32 v148, v9, v6
	v_cvt_pk_bf16_f32 v149, v10, v7
	v_or_b32_e32 v1, s1, v196
	v_add_lshl_u32 v4, v1, s39, 5
	v_ashrrev_i32_e32 v5, 31, v4
	v_lshlrev_b64 v[4:5], 2, v[4:5]
	v_lshl_add_u64 v[10:11], s[34:35], 0, v[4:5]
	v_lshl_add_u64 v[12:13], s[86:87], 0, v[4:5]
	v_lshl_add_u64 v[4:5], v[10:11], 0, v[194:195]
	v_lshl_add_u64 v[18:19], v[12:13], 0, v[194:195]
	s_add_i32 s1, 0, 0x18000
	v_add_u32_e32 v206, s1, v205
	s_waitcnt vmcnt(4)
	v_lshlrev_b32_e32 v1, 16, v158
	v_and_b32_e32 v6, 0xffff0000, v158
	v_lshlrev_b32_e32 v10, 16, v159
	v_and_b32_e32 v7, 0xffff0000, v159
	v_lshlrev_b32_e32 v11, 16, v160
	v_and_b32_e32 v8, 0xffff0000, v160
	v_lshlrev_b32_e32 v14, 16, v161
	v_and_b32_e32 v9, 0xffff0000, v161
	v_mul_f32_e32 v6, 0x3dd53b94, v6
	v_mul_f32_e32 v10, 0x3dd53b94, v10
	v_mul_f32_e32 v7, 0x3dd53b94, v7
	v_mul_f32_e32 v11, 0x3dd53b94, v11
	v_mul_f32_e32 v8, 0x3dd53b94, v8
	v_mul_f32_e32 v14, 0x3dd53b94, v14
	v_mul_f32_e32 v9, 0x3dd53b94, v9
	v_mul_f32_e32 v1, 0x3dd53b94, v1
	v_cvt_pk_bf16_f32 v158, v1, v6
	v_cvt_pk_bf16_f32 v159, v10, v7
	v_cvt_pk_bf16_f32 v160, v11, v8
	v_cvt_pk_bf16_f32 v161, v14, v9
	global_load_dwordx4 v[10:13], v[4:5], off
	global_load_dwordx4 v[14:17], v[18:19], off
	s_waitcnt vmcnt(1)
	v_mov_b32_e32 v22, v10
	s_waitcnt vmcnt(0)
	v_mov_b32_e32 v23, v14
	v_mov_b32_e32 v14, v11
	v_mov_b32_e32 v24, v12
	v_mov_b32_e32 v25, v16
	v_mov_b32_e32 v16, v13
	v_lshlrev_b32_e32 v20, 16, v162
	v_and_b32_e32 v21, 0xffff0000, v162
	v_lshlrev_b32_e32 v6, 16, v163
	v_and_b32_e32 v7, 0xffff0000, v163
	v_lshlrev_b32_e32 v10, 16, v164
	v_and_b32_e32 v11, 0xffff0000, v164
	v_lshlrev_b32_e32 v8, 16, v165
	v_and_b32_e32 v9, 0xffff0000, v165
	v_pk_mul_f32 v[12:13], v[22:23], s[6:7] op_sel_hi:[1,0]
	v_pk_mul_f32 v[14:15], v[14:15], s[6:7] op_sel_hi:[1,0]
	v_pk_mul_f32 v[22:23], v[24:25], s[6:7] op_sel_hi:[1,0]
	v_pk_mul_f32 v[16:17], v[16:17], s[6:7] op_sel_hi:[1,0]
	v_pk_mul_f32 v[24:25], v[12:13], v[20:21]
	v_pk_mul_f32 v[12:13], v[12:13], v[20:21] op_sel:[0,1] op_sel_hi:[1,0]
	v_pk_mul_f32 v[20:21], v[14:15], v[6:7]
	v_pk_mul_f32 v[6:7], v[14:15], v[6:7] op_sel:[0,1] op_sel_hi:[1,0]
	v_pk_mul_f32 v[14:15], v[22:23], v[10:11]
	v_pk_mul_f32 v[10:11], v[22:23], v[10:11] op_sel:[0,1] op_sel_hi:[1,0]
	v_pk_mul_f32 v[22:23], v[16:17], v[8:9]
	v_pk_mul_f32 v[8:9], v[16:17], v[8:9] op_sel:[0,1] op_sel_hi:[1,0]
	v_add_f32_e32 v12, v12, v13
	v_sub_f32_e32 v13, v20, v21
	v_add_f32_e32 v6, v6, v7
	v_sub_f32_e32 v7, v14, v15
	v_add_f32_e32 v10, v10, v11
	v_sub_f32_e32 v11, v22, v23
	v_add_f32_e32 v8, v8, v9
	v_sub_f32_e32 v1, v24, v25
	v_cvt_pk_bf16_f32 v162, v1, v12
	v_cvt_pk_bf16_f32 v163, v13, v6
	v_cvt_pk_bf16_f32 v164, v7, v10
	v_cvt_pk_bf16_f32 v165, v11, v8
	global_load_dwordx4 v[10:13], v[4:5], off offset:32
	global_load_dwordx4 v[14:17], v[18:19], off offset:32
	s_waitcnt vmcnt(2)
	v_lshlrev_b32_e32 v20, 16, v166
	s_waitcnt vmcnt(1)
	v_mov_b32_e32 v22, v10
	s_waitcnt vmcnt(0)
	v_mov_b32_e32 v23, v14
	v_mov_b32_e32 v14, v11
	v_mov_b32_e32 v24, v12
	v_mov_b32_e32 v25, v16
	v_mov_b32_e32 v16, v13
	v_and_b32_e32 v21, 0xffff0000, v166
	v_lshlrev_b32_e32 v6, 16, v167
	v_and_b32_e32 v7, 0xffff0000, v167
	v_lshlrev_b32_e32 v10, 16, v168
	v_and_b32_e32 v11, 0xffff0000, v168
	v_lshlrev_b32_e32 v8, 16, v169
	v_and_b32_e32 v9, 0xffff0000, v169
	v_pk_mul_f32 v[12:13], v[22:23], s[6:7] op_sel_hi:[1,0]
	v_pk_mul_f32 v[14:15], v[14:15], s[6:7] op_sel_hi:[1,0]
	v_pk_mul_f32 v[22:23], v[24:25], s[6:7] op_sel_hi:[1,0]
	v_pk_mul_f32 v[16:17], v[16:17], s[6:7] op_sel_hi:[1,0]
	v_pk_mul_f32 v[24:25], v[12:13], v[20:21]
	v_pk_mul_f32 v[12:13], v[12:13], v[20:21] op_sel:[0,1] op_sel_hi:[1,0]
	v_pk_mul_f32 v[20:21], v[14:15], v[6:7]
	v_pk_mul_f32 v[6:7], v[14:15], v[6:7] op_sel:[0,1] op_sel_hi:[1,0]
	v_pk_mul_f32 v[14:15], v[22:23], v[10:11]
	v_pk_mul_f32 v[10:11], v[22:23], v[10:11] op_sel:[0,1] op_sel_hi:[1,0]
	v_pk_mul_f32 v[22:23], v[16:17], v[8:9]
	v_pk_mul_f32 v[8:9], v[16:17], v[8:9] op_sel:[0,1] op_sel_hi:[1,0]
	v_add_f32_e32 v12, v12, v13
	v_sub_f32_e32 v13, v20, v21
	v_add_f32_e32 v6, v6, v7
	v_sub_f32_e32 v7, v14, v15
	v_add_f32_e32 v10, v10, v11
	v_sub_f32_e32 v11, v22, v23
	v_add_f32_e32 v8, v8, v9
	v_sub_f32_e32 v1, v24, v25
	v_cvt_pk_bf16_f32 v166, v1, v12
	v_cvt_pk_bf16_f32 v167, v13, v6
	v_cvt_pk_bf16_f32 v168, v7, v10
	v_cvt_pk_bf16_f32 v169, v11, v8
	global_load_dwordx4 v[10:13], v[4:5], off offset:64
	global_load_dwordx4 v[14:17], v[18:19], off offset:64
	s_waitcnt vmcnt(2)
	v_lshlrev_b32_e32 v20, 16, v170
	s_waitcnt vmcnt(1)
	v_mov_b32_e32 v22, v10
	s_waitcnt vmcnt(0)
; __device__ __forceinline__ float bf2f(unsigned h) { return __uint_as_float(h << 16); }
; __device__ __forceinline__ void qkt192n(f32x16& p0, f32x16& p1, const char* Ks, const char* Kr, const bf16x8* qr, const f32x16& negm, int r32, int hi) {
; #pragma unroll
;   for (int d0 = 0; d0 < 8; ++d0) { const int cb = d0 * 32 + hi * 16;
;     const bf16x8 b0 = *reinterpret_cast<const bf16x8*>(Ks + KSWZ(r32, cb));
;     const bf16x8 b1 = *reinterpret_cast<const bf16x8*>(Ks + KSWZ(32 + r32, cb));
;     if (d0 == 0) { p0 = __builtin_amdgcn_mfma_f32_32x32x16_bf16(b0, qr[0], negm, 0, 0, 0); p1 = __builtin_amdgcn_mfma_f32_32x32x16_bf16(b1, qr[0], negm, 0, 0, 0); }
;     else { p0 = __builtin_amdgcn_mfma_f32_32x32x16_bf16(b0, qr[d0], p0, 0, 0, 0); p1 = __builtin_amdgcn_mfma_f32_32x32x16_bf16(b1, qr[d0], p1, 0, 0, 0); } }
; #pragma unroll
;   for (int d0 = 0; d0 < 4; ++d0) { const int cb = d0 * 32 + hi * 16;
;     const bf16x8 b0 = *reinterpret_cast<const bf16x8*>(Kr + RSWZ(r32, cb));
;     const bf16x8 b1 = *reinterpret_cast<const bf16x8*>(Kr + RSWZ(32 + r32, cb));
;     p0 = __builtin_amdgcn_mfma_f32_32x32x16_bf16(b0, qr[8 + d0], p0, 0, 0, 0);
;     p1 = __builtin_amdgcn_mfma_f32_32x32x16_bf16(b1, qr[8 + d0], p1, 0, 0, 0); }
; __device__ __forceinline__ void mla_unit(char* lds, const bf16_t* __restrict__ Qp, const bf16_t* __restrict__ Knp, const bf16_t* __restrict__ Vp, ...
;     ...
;     for (int d0 = 0; d0 < 4; ++d0) {
;       const u32x4 raw = *reinterpret_cast<const u32x4*>(Qw + 128 + d0 * 16);
;       const int i0 = d0 * 8 + hi * 4;
;       const f32x4 cc = *reinterpret_cast<const f32x4*>(cs_tab + pos * 32 + i0) * C, ss = *reinterpret_cast<const f32x4*>(sn_tab + pos * 32 + i0) * C;
;       u32x4 w;
; #pragma unroll
;       for (int p = 0; p < 4; ++p) { const float x1 = bf2f(raw[p] & 0xffffu), x2 = bf2f(raw[p] >> 16); w[p] = cvtpk(x1 * cc[p] - x2 * ss[p], x1 * ss[p] + x2 * cc[p]); }
;       qr[8 + d0] = *reinterpret_cast<bf16x8*>(&w);
;     } }
	v_mov_b32_e32 v23, v14
	v_mov_b32_e32 v14, v11
	v_mov_b32_e32 v24, v12
	v_mov_b32_e32 v25, v16
	v_mov_b32_e32 v16, v13
	v_and_b32_e32 v21, 0xffff0000, v170
	v_lshlrev_b32_e32 v6, 16, v171
	v_and_b32_e32 v7, 0xffff0000, v171
	v_lshlrev_b32_e32 v10, 16, v172
	v_and_b32_e32 v11, 0xffff0000, v172
	v_lshlrev_b32_e32 v8, 16, v173
	v_and_b32_e32 v9, 0xffff0000, v173
	v_pk_mul_f32 v[12:13], v[22:23], s[6:7] op_sel_hi:[1,0]
	v_pk_mul_f32 v[14:15], v[14:15], s[6:7] op_sel_hi:[1,0]
	v_pk_mul_f32 v[22:23], v[24:25], s[6:7] op_sel_hi:[1,0]
	v_pk_mul_f32 v[16:17], v[16:17], s[6:7] op_sel_hi:[1,0]
	v_pk_mul_f32 v[24:25], v[12:13], v[20:21]
	v_pk_mul_f32 v[12:13], v[12:13], v[20:21] op_sel:[0,1] op_sel_hi:[1,0]
	v_pk_mul_f32 v[20:21], v[14:15], v[6:7]
	v_pk_mul_f32 v[6:7], v[14:15], v[6:7] op_sel:[0,1] op_sel_hi:[1,0]
	v_pk_mul_f32 v[14:15], v[22:23], v[10:11]
	v_pk_mul_f32 v[10:11], v[22:23], v[10:11] op_sel:[0,1] op_sel_hi:[1,0]
	v_pk_mul_f32 v[22:23], v[16:17], v[8:9]
	v_pk_mul_f32 v[8:9], v[16:17], v[8:9] op_sel:[0,1] op_sel_hi:[1,0]
	v_sub_f32_e32 v1, v24, v25
	v_add_f32_e32 v12, v12, v13
	v_sub_f32_e32 v13, v20, v21
	v_add_f32_e32 v6, v6, v7
	v_sub_f32_e32 v7, v14, v15
	v_add_f32_e32 v10, v10, v11
	v_sub_f32_e32 v11, v22, v23
	v_add_f32_e32 v8, v8, v9
	v_cvt_pk_bf16_f32 v170, v1, v12
	v_cvt_pk_bf16_f32 v171, v13, v6
	v_cvt_pk_bf16_f32 v172, v7, v10
	v_cvt_pk_bf16_f32 v173, v11, v8
	global_load_dwordx4 v[36:39], v[4:5], off offset:96
	global_load_dwordx4 v[40:43], v[18:19], off offset:96
	v_mov_b32_e32 v14, v0
	v_mov_b32_e32 v15, v0
	v_mov_b32_e32 v1, v0
	v_mov_b32_e32 v2, v0
	v_mov_b32_e32 v3, v0
	v_mov_b32_e32 v4, v0
	v_mov_b32_e32 v5, v0
	v_mov_b32_e32 v6, v0
	v_mov_b32_e32 v7, v0
	v_mov_b32_e32 v8, v0
	v_mov_b32_e32 v9, v0
	v_mov_b32_e32 v10, v0
	v_mov_b32_e32 v11, v0
	v_mov_b32_e32 v12, v0
	v_mov_b32_e32 v13, v0
	v_mov_b64_e32 v[30:31], v[14:15]
	v_mov_b64_e32 v[28:29], v[12:13]
	v_mov_b64_e32 v[26:27], v[10:11]
	v_mov_b64_e32 v[24:25], v[8:9]
	v_mov_b64_e32 v[22:23], v[6:7]
	v_mov_b64_e32 v[20:21], v[4:5]
	v_mov_b64_e32 v[18:19], v[2:3]
	v_mov_b64_e32 v[16:17], v[0:1]
	s_waitcnt vmcnt(2)
	v_lshlrev_b32_e32 v44, 16, v174
	s_waitcnt vmcnt(1)
	v_mov_b32_e32 v46, v36
	s_waitcnt vmcnt(0)
	v_mov_b32_e32 v47, v40
	v_mov_b32_e32 v40, v37
	v_mov_b32_e32 v52, v38
	v_mov_b32_e32 v53, v42
	v_mov_b32_e32 v42, v39
	v_and_b32_e32 v45, 0xffff0000, v174
	v_lshlrev_b32_e32 v32, 16, v175
	v_and_b32_e32 v33, 0xffff0000, v175
	v_lshlrev_b32_e32 v36, 16, v176
	v_and_b32_e32 v37, 0xffff0000, v176
	v_lshlrev_b32_e32 v34, 16, v177
	v_and_b32_e32 v35, 0xffff0000, v177
	v_pk_mul_f32 v[38:39], v[46:47], s[6:7] op_sel_hi:[1,0]
	v_pk_mul_f32 v[40:41], v[40:41], s[6:7] op_sel_hi:[1,0]
	v_pk_mul_f32 v[46:47], v[52:53], s[6:7] op_sel_hi:[1,0]
	v_pk_mul_f32 v[42:43], v[42:43], s[6:7] op_sel_hi:[1,0]
	v_pk_mul_f32 v[52:53], v[38:39], v[44:45]
	v_pk_mul_f32 v[38:39], v[38:39], v[44:45] op_sel:[0,1] op_sel_hi:[1,0]
	v_pk_mul_f32 v[44:45], v[40:41], v[32:33]
	v_pk_mul_f32 v[32:33], v[40:41], v[32:33] op_sel:[0,1] op_sel_hi:[1,0]
	v_pk_mul_f32 v[40:41], v[46:47], v[36:37]
	v_pk_mul_f32 v[36:37], v[46:47], v[36:37] op_sel:[0,1] op_sel_hi:[1,0]
	v_pk_mul_f32 v[46:47], v[42:43], v[34:35]
	v_pk_mul_f32 v[34:35], v[42:43], v[34:35] op_sel:[0,1] op_sel_hi:[1,0]
	v_sub_f32_e32 v42, v52, v53
	v_add_f32_e32 v38, v38, v39
	v_sub_f32_e32 v39, v44, v45
	v_add_f32_e32 v32, v32, v33
	v_sub_f32_e32 v33, v40, v41
	v_add_f32_e32 v36, v36, v37
	v_sub_f32_e32 v37, v46, v47
	v_add_f32_e32 v34, v34, v35
	v_cvt_pk_bf16_f32 v174, v42, v38
	v_cvt_pk_bf16_f32 v175, v39, v32
	v_cvt_pk_bf16_f32 v176, v33, v36
	v_cvt_pk_bf16_f32 v177, v37, v34
	s_waitcnt vmcnt(10) lgkmcnt(0)
	s_barrier
	ds_read_b128 v[52:55], v56 offset:49152
	ds_read_b128 v[56:59], v56 offset:57344
	s_waitcnt lgkmcnt(1)
	v_mfma_f32_32x32x16_bf16 v[32:47], v[52:55], v[130:133], v[16:31]
	v_or_b32_e32 v52, 32, v194
	v_xad_u32 v53, v52, v51, v66
	s_waitcnt lgkmcnt(0)
	v_mfma_f32_32x32x16_bf16 v[16:31], v[56:59], v[130:133], v[16:31]
	ds_read_b128 v[54:57], v53 offset:49152
	ds_read_b128 v[58:61], v53 offset:57344
	v_or_b32_e32 v53, 64, v194
	v_xad_u32 v62, v53, v51, v66
	s_waitcnt lgkmcnt(1)
	v_mfma_f32_32x32x16_bf16 v[32:47], v[54:57], v[134:137], v[32:47]
	s_waitcnt lgkmcnt(0)
	v_mfma_f32_32x32x16_bf16 v[16:31], v[58:61], v[134:137], v[16:31]
	ds_read_b128 v[54:57], v62 offset:49152
	ds_read_b128 v[58:61], v62 offset:57344
	s_waitcnt lgkmcnt(1)
	v_mfma_f32_32x32x16_bf16 v[32:47], v[54:57], v[138:141], v[32:47]
	v_or_b32_e32 v54, 0x60, v194
	v_xad_u32 v55, v54, v51, v66
	s_waitcnt lgkmcnt(0)
	v_mfma_f32_32x32x16_bf16 v[16:31], v[58:61], v[138:141], v[16:31]
	ds_read_b128 v[56:59], v55 offset:49152
	ds_read_b128 v[60:63], v55 offset:57344
	v_or_b32_e32 v55, 0x80, v194
	v_xad_u32 v64, v55, v51, v66
	s_waitcnt lgkmcnt(1)
	v_mfma_f32_32x32x16_bf16 v[32:47], v[56:59], v[142:145], v[32:47]
	s_waitcnt lgkmcnt(0)
	v_mfma_f32_32x32x16_bf16 v[16:31], v[60:63], v[142:145], v[16:31]
	ds_read_b128 v[56:59], v64 offset:49152
	ds_read_b128 v[60:63], v64 offset:57344
	s_waitcnt lgkmcnt(1)
	v_mfma_f32_32x32x16_bf16 v[32:47], v[56:59], v[154:157], v[32:47]
	v_or_b32_e32 v56, 0xa0, v194
	v_xad_u32 v57, v56, v51, v66
	s_waitcnt lgkmcnt(0)
	v_mfma_f32_32x32x16_bf16 v[16:31], v[60:63], v[154:157], v[16:31]
	ds_read_b128 v[58:61], v57 offset:49152
	ds_read_b128 v[62:65], v57 offset:57344
	v_or_b32_e32 v57, 0xc0, v194
	v_xad_u32 v67, v57, v51, v66
	s_waitcnt lgkmcnt(1)
	v_mfma_f32_32x32x16_bf16 v[32:47], v[58:61], v[150:153], v[32:47]
	s_waitcnt lgkmcnt(0)
	v_mfma_f32_32x32x16_bf16 v[16:31], v[62:65], v[150:153], v[16:31]
	ds_read_b128 v[58:61], v67 offset:49152
	ds_read_b128 v[62:65], v67 offset:57344
	s_waitcnt lgkmcnt(1)
; __device__ __forceinline__ void qkt192n(f32x16& p0, f32x16& p1, const char* Ks, const char* Kr, const bf16x8* qr, const f32x16& negm, int r32, int hi) {
; #pragma unroll
;   for (int d0 = 0; d0 < 8; ++d0) { const int cb = d0 * 32 + hi * 16;
;     const bf16x8 b0 = *reinterpret_cast<const bf16x8*>(Ks + KSWZ(r32, cb));
;     const bf16x8 b1 = *reinterpret_cast<const bf16x8*>(Ks + KSWZ(32 + r32, cb));
;     if (d0 == 0) { p0 = __builtin_amdgcn_mfma_f32_32x32x16_bf16(b0, qr[0], negm, 0, 0, 0); p1 = __builtin_amdgcn_mfma_f32_32x32x16_bf16(b1, qr[0], negm, 0, 0, 0); }
;     else { p0 = __builtin_amdgcn_mfma_f32_32x32x16_bf16(b0, qr[d0], p0, 0, 0, 0); p1 = __builtin_amdgcn_mfma_f32_32x32x16_bf16(b1, qr[d0], p1, 0, 0, 0); } }
; #pragma unroll
;   for (int d0 = 0; d0 < 4; ++d0) { const int cb = d0 * 32 + hi * 16;
;     const bf16x8 b0 = *reinterpret_cast<const bf16x8*>(Kr + RSWZ(r32, cb));
;     const bf16x8 b1 = *reinterpret_cast<const bf16x8*>(Kr + RSWZ(32 + r32, cb));
;     p0 = __builtin_amdgcn_mfma_f32_32x32x16_bf16(b0, qr[8 + d0], p0, 0, 0, 0);
;     p1 = __builtin_amdgcn_mfma_f32_32x32x16_bf16(b1, qr[8 + d0], p1, 0, 0, 0); }
	v_mfma_f32_32x32x16_bf16 v[32:47], v[58:61], v[146:149], v[32:47]
	v_or_b32_e32 v58, 0xe0, v194
	v_xad_u32 v59, v58, v51, v66
	s_waitcnt lgkmcnt(0)
	v_mfma_f32_32x32x16_bf16 v[16:31], v[62:65], v[146:149], v[16:31]
	ds_read_b128 v[60:63], v59 offset:49152
	ds_read_b128 v[64:67], v59 offset:57344
	v_lshlrev_b32_e32 v59, 3, v50
	v_and_b32_e32 v68, 0x70, v59
	v_xad_u32 v69, v194, v68, v206
	v_and_b32_e32 v50, 63, v50
	v_cmp_gt_u32_e64 s[40:41], 32, v50
	s_waitcnt lgkmcnt(1)
	v_mfma_f32_32x32x16_bf16 v[32:47], v[60:63], v[158:161], v[32:47]
	s_waitcnt lgkmcnt(0)
	v_mfma_f32_32x32x16_bf16 v[16:31], v[64:67], v[158:161], v[16:31]
	ds_read_b128 v[60:63], v69
	ds_read_b128 v[64:67], v69 offset:4096
	v_xad_u32 v69, v52, v68, v206
	s_waitcnt lgkmcnt(1)
	v_mfma_f32_32x32x16_bf16 v[32:47], v[60:63], v[162:165], v[32:47]
	s_waitcnt lgkmcnt(0)
	v_mfma_f32_32x32x16_bf16 v[16:31], v[64:67], v[162:165], v[16:31]
	ds_read_b128 v[60:63], v69
	ds_read_b128 v[64:67], v69 offset:4096
	v_xad_u32 v69, v53, v68, v206
	v_xad_u32 v68, v54, v68, v206
	s_waitcnt lgkmcnt(1)
	v_mfma_f32_32x32x16_bf16 v[32:47], v[60:63], v[166:169], v[32:47]
	s_waitcnt lgkmcnt(0)
	v_mfma_f32_32x32x16_bf16 v[16:31], v[64:67], v[166:169], v[16:31]
	ds_read_b128 v[60:63], v69
	ds_read_b128 v[64:67], v69 offset:4096
	s_waitcnt lgkmcnt(1)
	v_mfma_f32_32x32x16_bf16 v[32:47], v[60:63], v[170:173], v[32:47]
	s_waitcnt lgkmcnt(0)
	v_mfma_f32_32x32x16_bf16 v[16:31], v[64:67], v[170:173], v[16:31]
	ds_read_b128 v[60:63], v68
	ds_read_b128 v[64:67], v68 offset:4096
	s_waitcnt lgkmcnt(1)
	v_mfma_f32_32x32x16_bf16 v[32:47], v[60:63], v[174:177], v[32:47]
	s_waitcnt lgkmcnt(0)
	v_mfma_f32_32x32x16_bf16 v[16:31], v[64:67], v[174:177], v[16:31]
	s_nop 9
	v_max_f32_e32 v60, v33, v33
	v_max_f32_e32 v61, v32, v32
	v_max_f32_e32 v60, v61, v60
	v_max3_f32 v62, v34, v35, v17
	v_max3_f32 v60, v60, v16, v18
	v_max3_f32 v61, v62, v38, v39
	v_max3_f32 v60, v60, v19, v36
	v_max3_f32 v61, v61, v22, v23
	v_max3_f32 v60, v60, v37, v20
	v_max3_f32 v61, v61, v42, v43
	v_max3_f32 v60, v60, v21, v40
	v_max3_f32 v61, v61, v26, v27
	v_max3_f32 v60, v60, v41, v24
	v_max3_f32 v61, v61, v46, v47
	v_max3_f32 v60, v60, v25, v44
	v_max3_f32 v61, v61, v30, v31
	v_max3_f32 v60, v60, v45, v28
	v_max3_f32 v60, v60, v29, v61
	v_mov_b32_e32 v61, v60
	s_nop 1
	v_permlane32_swap_b32_e32 v60, v61
	v_max_f32_e32 v61, v61, v61
	v_max_f32_e32 v60, v60, v60
	v_max_f32_e32 v61, v60, v61
	v_exp_f32_e64 v60, -v61
	v_add_f32_e32 v203, 0, v61
	v_xor_b32_e32 v66, 0x80000000, v203
	v_mov_b32_e32 v67, v66
	v_mov_b32_e32 v68, v66
	v_mov_b32_e32 v69, v66
	v_mov_b32_e32 v70, v66
	v_mov_b32_e32 v71, v66
	v_mov_b32_e32 v72, v66
	v_mov_b32_e32 v73, v66
	v_mov_b32_e32 v74, v66
	v_mov_b32_e32 v75, v66
	v_mov_b32_e32 v76, v66
	v_mov_b32_e32 v77, v66
	v_mov_b32_e32 v78, v66
	v_mov_b32_e32 v79, v66
	v_mov_b32_e32 v80, v66
	v_mov_b32_e32 v81, v66
	s_and_saveexec_b64 s[6:7], s[40:41]
	ds_write_b32 v200, v60 offset:128
	s_or_b64 exec, exec, s[6:7]
	v_sub_f32_e32 v32, v32, v61
	v_sub_f32_e32 v33, v33, v61
	v_sub_f32_e32 v82, v16, v61
	v_exp_f32_e32 v16, v32
	v_sub_f32_e32 v34, v34, v61
	v_sub_f32_e32 v83, v17, v61
	v_exp_f32_e32 v17, v33
	v_sub_f32_e32 v35, v35, v61
	v_sub_f32_e32 v84, v18, v61
	v_exp_f32_e32 v18, v34
	v_sub_f32_e32 v36, v36, v61
	v_sub_f32_e32 v85, v19, v61
	v_exp_f32_e32 v19, v35
	v_sub_f32_e32 v37, v37, v61
	v_sub_f32_e32 v86, v20, v61
	v_exp_f32_e32 v20, v36
	v_add_f32_e32 v32, 0, v16
	v_sub_f32_e32 v38, v38, v61
	v_sub_f32_e32 v87, v21, v61
	v_exp_f32_e32 v21, v37
	v_add_f32_e32 v32, v17, v32
	v_sub_f32_e32 v39, v39, v61
	v_sub_f32_e32 v88, v22, v61
	v_exp_f32_e32 v22, v38
	v_add_f32_e32 v32, v18, v32
	v_sub_f32_e32 v40, v40, v61
	v_sub_f32_e32 v89, v23, v61
	v_exp_f32_e32 v23, v39
	v_add_f32_e32 v32, v19, v32
	v_sub_f32_e32 v41, v41, v61
	v_sub_f32_e32 v90, v24, v61
	v_exp_f32_e32 v24, v40
	v_add_f32_e32 v32, v20, v32
	v_sub_f32_e32 v42, v42, v61
	v_sub_f32_e32 v91, v25, v61
	v_exp_f32_e32 v25, v41
	v_add_f32_e32 v32, v21, v32
	v_sub_f32_e32 v43, v43, v61
	v_sub_f32_e32 v92, v26, v61
	v_exp_f32_e32 v26, v42
	v_add_f32_e32 v32, v22, v32
	v_sub_f32_e32 v44, v44, v61
	v_sub_f32_e32 v93, v27, v61
	v_exp_f32_e32 v27, v43
	v_add_f32_e32 v32, v23, v32
	v_sub_f32_e32 v45, v45, v61
	v_sub_f32_e32 v94, v28, v61
	v_exp_f32_e32 v28, v44
	v_add_f32_e32 v32, v24, v32
	s_lshr_b32 s69, s74, 5
	v_sub_f32_e32 v46, v46, v61
	v_sub_f32_e32 v95, v29, v61
	v_exp_f32_e32 v29, v45
	v_add_f32_e32 v32, v25, v32
	v_sub_f32_e32 v47, v47, v61
	v_sub_f32_e32 v96, v30, v61
	s_and_b32 s0, s69, 15
	v_exp_f32_e32 v30, v46
	v_add_f32_e32 v32, v26, v32
	s_movk_i32 s1, 0x70
	v_sub_f32_e32 v97, v31, v61
	s_lshl_b32 s0, s0, 23
	v_exp_f32_e32 v31, v47
	v_add_f32_e32 v32, v27, v32
	v_bitop3_b32 v221, v194, v59, s1 bitop3:0x78
	v_bitop3_b32 v209, v52, v59, s1 bitop3:0x78
	v_bitop3_b32 v208, v53, v59, s1 bitop3:0x78
	v_bitop3_b32 v207, v54, v59, s1 bitop3:0x78
	v_readlane_b32 s1, v254, 9
	v_lshlrev_b32_e32 v62, 4, v50
	v_add_f32_e32 v32, v28, v32
	s_add_u32 s36, s1, s36
	v_readlane_b32 s1, v254, 10
	v_lshlrev_b32_e32 v195, 2, v49
	v_lshlrev_b32_e32 v49, 3, v50
	v_and_b32_e32 v62, 0xc0, v62
	v_lshlrev_b32_e32 v50, 1, v50
	v_add_f32_e32 v32, v29, v32
	s_addc_u32 s37, s1, s37
	v_and_or_b32 v62, v49, 24, v62
	v_and_b32_e32 v50, 32, v50
	v_and_b32_e32 v49, 0x100, v49
	v_add_f32_e32 v32, v30, v32
	s_add_u32 s0, s0, s30
	v_or3_b32 v201, v62, v50, v49
	v_mul_f32_e32 v234, 0, v60
	v_add_f32_e32 v186, v31, v32
	v_cvt_pk_bf16_f32 v182, v16, v17
	v_cvt_pk_bf16_f32 v183, v18, v19
	v_cvt_pk_bf16_f32 v184, v20, v21
	v_cvt_pk_bf16_f32 v185, v22, v23
	v_cvt_pk_bf16_f32 v178, v24, v25
	v_cvt_pk_bf16_f32 v179, v26, v27
	v_cvt_pk_bf16_f32 v180, v28, v29
	v_cvt_pk_bf16_f32 v181, v30, v31
	v_bitop3_b32 v229, v194, v48, s53 bitop3:0x78
	v_bitop3_b32 v230, v194, v204, v51 bitop3:0xde
	v_bitop3_b32 v228, v52, v48, s53 bitop3:0x78
	v_bitop3_b32 v231, v52, v204, v51 bitop3:0xde
	v_bitop3_b32 v227, v53, v48, s53 bitop3:0x78
	v_bitop3_b32 v226, v54, v48, s53 bitop3:0x78
	v_bitop3_b32 v225, v55, v48, s53 bitop3:0x78
	v_bitop3_b32 v224, v56, v48, s53 bitop3:0x78
	v_bitop3_b32 v223, v57, v48, s53 bitop3:0x78
	v_bitop3_b32 v222, v58, v48, s53 bitop3:0x78
	s_addc_u32 s1, 0, s31
	v_readlane_b32 s12, v254, 35
	v_mov_b64_e32 v[64:65], v[14:15]
	v_mov_b64_e32 v[48:49], v[14:15]
	v_mov_b64_e32 v[32:33], v[14:15]
	v_readlane_b32 s13, v254, 36
	s_add_u32 s30, s12, s0
	v_mov_b64_e32 v[62:63], v[12:13]
	v_mov_b64_e32 v[60:61], v[10:11]
	v_mov_b64_e32 v[58:59], v[8:9]
	v_mov_b64_e32 v[56:57], v[6:7]
	v_mov_b64_e32 v[54:55], v[4:5]
	v_mov_b64_e32 v[52:53], v[2:3]
	v_mov_b64_e32 v[50:51], v[0:1]
	v_mov_b64_e32 v[46:47], v[12:13]
	v_mov_b64_e32 v[44:45], v[10:11]
	v_mov_b64_e32 v[42:43], v[8:9]
	v_mov_b64_e32 v[40:41], v[6:7]
	v_mov_b64_e32 v[38:39], v[4:5]
	v_mov_b64_e32 v[36:37], v[2:3]
	v_mov_b64_e32 v[34:35], v[0:1]
	v_mov_b64_e32 v[30:31], v[12:13]
	v_mov_b64_e32 v[28:29], v[10:11]
	v_mov_b64_e32 v[26:27], v[8:9]
	v_mov_b64_e32 v[24:25], v[6:7]
	v_mov_b64_e32 v[22:23], v[4:5]
	v_mov_b64_e32 v[20:21], v[2:3]
	v_mov_b64_e32 v[18:19], v[0:1]
	v_mov_b64_e32 v[16:17], v[14:15]
	s_mov_b32 s70, 1
	v_add_u32_e32 v202, 0, v201
	v_permlane32_swap_b32_e32 v182, v184
	v_permlane32_swap_b32_e32 v183, v185
	v_permlane32_swap_b32_e32 v178, v180
	v_permlane32_swap_b32_e32 v179, v181
	s_mov_b32 s77, 2
	v_add_u32_e32 v232, v229, v204
	v_add_u32_e32 v233, v228, v204
	s_addc_u32 s31, s13, s1
	s_mov_b32 s78, 0
	v_mov_b64_e32 v[14:15], v[12:13]
	v_mov_b64_e32 v[12:13], v[10:11]
	v_mov_b64_e32 v[10:11], v[8:9]
	v_mov_b64_e32 v[8:9], v[6:7]
	v_mov_b64_e32 v[6:7], v[4:5]
	v_mov_b64_e32 v[4:5], v[2:3]
	v_mov_b64_e32 v[2:3], v[0:1]
	s_mov_b32 s0, 0
	v_readlane_b32 s14, v254, 37
	v_readlane_b32 s15, v254, 38
